# removed compiler vmcnt(0) at epilogue start of phases 1/3/12 (row stats already retired by K-loop counted waits)
# speedup vs baseline: 1.0032x; 1.0032x over previous
; __device__ __forceinline__ float sigmoid_f(float x) { return __builtin_amdgcn_rcpf(1.0f + __builtin_amdgcn_exp2f(-x * LOG2E)); }
; __device__ __forceinline__ u32x4 pack8(const f32x4 a, const f32x4 b) { u32x4 w; w.x = cvt_pk_bf16(a[0], a[1]); w.y = cvt_pk_bf16(a[2], a[3]); w.z = cvt_pk_bf16(b[0], b[1]); w.w = cvt_pk_bf16(b[2], b[3]); return w; }
;     __device__ __forceinline__ void operator()(const Acc& acc, const Unit& u, int wr, int wc, int fr, int fq, const float (&sv8)[8]) const {
;         const int col0 = u.pn * 128 + wc * 32 + 8 * fq, rowb = u.pm * 256 + wr * 64 + fr;
; #pragma unroll
;         for (int ai = 0; ai < 2; ++ai)
; #pragma unroll
;             for (int m = 0; m < 4; ++m) {
;                 const int row = rowb + ai * 128 + m * 16;
;                 const float rs = rsqrtf(sv8[ai * 4 + m] * (1.0f / DM) + EPS);
;                 f32x4 h[2];
; #pragma unroll
;                 for (int n = 0; n < 2; ++n)
; #pragma unroll
;                     for (int j = 0; j < 4; ++j) { const float gv = acc[ai][0][m][n][j] * rs, uv = acc[ai][1][m][n][j] * rs; h[n][j] = gv * sigmoid_f(gv) * uv; }
;                 __builtin_nontemporal_store(pack8(h[0], h[1]), (u32x4*)(H + (size_t)row * FF + col0));
.LBB0_160:
	v_fmamk_f32 v128, v236, 0x3a000000, v227
	v_mul_f32_e32 v129, 0x4b800000, v128
	v_cmp_gt_f32_e32 vcc, s54, v128
	s_nop 1
	v_cndmask_b32_e32 v128, v128, v129, vcc
	v_rsq_f32_e32 v130, v128
	v_lshl_or_b32 v128, s56, 7, v223
	v_ashrrev_i32_e32 v129, 31, v128
	v_mul_f32_e32 v131, 0x45800000, v130
	v_cndmask_b32_e32 v130, v130, v131, vcc
	v_pk_mul_f32 v[124:125], v[124:125], v[130:131] op_sel_hi:[1,0]
	s_nop 0
	v_mul_f32_e32 v131, 0xbfb8aa3b, v124
	v_exp_f32_e32 v131, v131
	v_mul_f32_e32 v132, 0xbfb8aa3b, v125
	v_exp_f32_e32 v133, v132
	v_pk_mul_f32 v[120:121], v[120:121], v[130:131] op_sel_hi:[1,0]
	v_add_f32_e32 v131, 1.0, v131
	v_rcp_f32_e32 v132, v131
	v_add_f32_e32 v131, 1.0, v133
	v_pk_mul_f32 v[126:127], v[126:127], v[130:131] op_sel_hi:[1,0]
	s_nop 0
	v_mul_f32_e32 v133, 0xbfb8aa3b, v126
	v_exp_f32_e32 v134, v133
	v_mul_f32_e32 v133, 0xbfb8aa3b, v127
	v_exp_f32_e32 v135, v133
	v_rcp_f32_e32 v133, v131
	v_add_f32_e32 v131, 1.0, v134
	v_rcp_f32_e32 v134, v131
	v_add_f32_e32 v131, 1.0, v135
	v_rcp_f32_e32 v135, v131
	v_pk_mul_f32 v[124:125], v[124:125], v[132:133]
	v_pk_mul_f32 v[116:117], v[116:117], v[130:131] op_sel_hi:[1,0]
	v_pk_mul_f32 v[120:121], v[120:121], v[124:125]
	v_pk_mul_f32 v[124:125], v[126:127], v[134:135]
	v_mul_f32_e32 v126, 0xbfb8aa3b, v116
	v_exp_f32_e32 v126, v126
	v_pk_mul_f32 v[122:123], v[122:123], v[130:131] op_sel_hi:[1,0]
	v_pk_mul_f32 v[118:119], v[118:119], v[130:131] op_sel_hi:[1,0]
	v_pk_mul_f32 v[122:123], v[122:123], v[124:125]
	v_mul_f32_e32 v124, 0xbfb8aa3b, v117
	v_exp_f32_e32 v125, v124
	v_add_f32_e32 v124, 1.0, v126
	v_mul_f32_e32 v126, 0xbfb8aa3b, v118
	v_mul_f32_e32 v127, 0xbfb8aa3b, v119
	v_exp_f32_e32 v126, v126
	v_exp_f32_e32 v127, v127
	v_add_f32_e32 v125, 1.0, v125
	v_rcp_f32_e32 v124, v124
	v_rcp_f32_e32 v125, v125
	v_add_f32_e32 v126, 1.0, v126
	v_add_f32_e32 v127, 1.0, v127
	v_rcp_f32_e32 v126, v126
	v_rcp_f32_e32 v127, v127
	v_pk_mul_f32 v[112:113], v[112:113], v[130:131] op_sel_hi:[1,0]
	v_pk_mul_f32 v[116:117], v[116:117], v[124:125]
	v_pk_mul_f32 v[114:115], v[114:115], v[130:131] op_sel_hi:[1,0]
	v_pk_mul_f32 v[112:113], v[112:113], v[116:117]
	v_pk_mul_f32 v[116:117], v[118:119], v[126:127]
	v_cvt_pk_bf16_f32 v118, v112, v113
	v_pk_mul_f32 v[114:115], v[114:115], v[116:117]
	v_cvt_pk_bf16_f32 v117, v122, v123
	v_cvt_pk_bf16_f32 v119, v114, v115
	v_fmamk_f32 v114, v235, 0x3a000000, v227
	v_mul_f32_e32 v115, 0x4b800000, v114
	v_cmp_gt_f32_e32 vcc, s54, v114
	v_mov_b64_e32 v[112:113], s[94:95]
	v_cvt_pk_bf16_f32 v116, v120, v121
	v_cndmask_b32_e32 v114, v114, v115, vcc
	v_rsq_f32_e32 v122, v114
	v_mad_i64_i32 v[120:121], s[28:29], v210, s55, v[112:113]
	v_lshlrev_b64 v[114:115], 1, v[128:129]
	v_mul_f32_e32 v123, 0x45800000, v122
	v_cndmask_b32_e32 v122, v122, v123, vcc
	v_pk_mul_f32 v[108:109], v[108:109], v[122:123] op_sel_hi:[1,0]
	v_lshl_add_u64 v[120:121], v[120:121], 0, v[114:115]
	v_mul_f32_e32 v123, 0xbfb8aa3b, v108
	v_exp_f32_e32 v123, v123
	global_store_dwordx4 v[120:121], v[116:119], off nt
	v_pk_mul_f32 v[110:111], v[110:111], v[122:123] op_sel_hi:[1,0]
	s_nop 0
	v_mul_f32_e32 v116, 0xbfb8aa3b, v109
	v_exp_f32_e32 v117, v116
	v_mul_f32_e32 v118, 0xbfb8aa3b, v110
	v_mul_f32_e32 v119, 0xbfb8aa3b, v111
	v_exp_f32_e32 v118, v118
	v_exp_f32_e32 v119, v119
	v_add_f32_e32 v116, 1.0, v123
	v_add_f32_e32 v117, 1.0, v117
	v_rcp_f32_e32 v116, v116
	v_rcp_f32_e32 v117, v117
	v_add_f32_e32 v118, 1.0, v118
	v_add_f32_e32 v119, 1.0, v119
	v_rcp_f32_e32 v118, v118
	v_rcp_f32_e32 v119, v119
	v_pk_mul_f32 v[104:105], v[104:105], v[122:123] op_sel_hi:[1,0]
	v_pk_mul_f32 v[108:109], v[108:109], v[116:117]
	v_pk_mul_f32 v[100:101], v[100:101], v[122:123] op_sel_hi:[1,0]
	v_pk_mul_f32 v[104:105], v[104:105], v[108:109]
	v_pk_mul_f32 v[108:109], v[110:111], v[118:119]
	v_mul_f32_e32 v110, 0xbfb8aa3b, v100
	v_exp_f32_e32 v110, v110
	v_pk_mul_f32 v[106:107], v[106:107], v[122:123] op_sel_hi:[1,0]
	v_pk_mul_f32 v[102:103], v[102:103], v[122:123] op_sel_hi:[1,0]
	v_pk_mul_f32 v[106:107], v[106:107], v[108:109]
	v_mul_f32_e32 v108, 0xbfb8aa3b, v101
	v_exp_f32_e32 v109, v108
	v_add_f32_e32 v108, 1.0, v110
	v_mul_f32_e32 v110, 0xbfb8aa3b, v102
	v_mul_f32_e32 v111, 0xbfb8aa3b, v103
	v_exp_f32_e32 v110, v110
	v_exp_f32_e32 v111, v111
	v_add_f32_e32 v109, 1.0, v109
	v_rcp_f32_e32 v108, v108
	v_rcp_f32_e32 v109, v109
	v_add_f32_e32 v110, 1.0, v110
	v_add_f32_e32 v111, 1.0, v111
	v_rcp_f32_e32 v110, v110
	v_rcp_f32_e32 v111, v111
	v_pk_mul_f32 v[96:97], v[96:97], v[122:123] op_sel_hi:[1,0]
	v_pk_mul_f32 v[100:101], v[100:101], v[108:109]
	v_or_b32_e32 v108, 16, v210
	v_pk_mul_f32 v[100:101], v[96:97], v[100:101]
	v_pk_mul_f32 v[96:97], v[98:99], v[122:123] op_sel_hi:[1,0]
	v_pk_mul_f32 v[98:99], v[102:103], v[110:111]
	s_nop 0
	v_pk_mul_f32 v[102:103], v[96:97], v[98:99]
	v_cvt_pk_bf16_f32 v98, v100, v101
	v_fmamk_f32 v100, v233, 0x3a000000, v227
	v_mul_f32_e32 v101, 0x4b800000, v100
	v_cmp_gt_f32_e32 vcc, s54, v100
	v_cvt_pk_bf16_f32 v99, v102, v103
	v_cvt_pk_bf16_f32 v96, v104, v105
	v_cndmask_b32_e32 v100, v100, v101, vcc
	v_rsq_f32_e32 v102, v100
	v_mad_i64_i32 v[100:101], s[28:29], v108, s55, v[112:113]
	v_cvt_pk_bf16_f32 v97, v106, v107
	v_mul_f32_e32 v103, 0x45800000, v102
	v_cndmask_b32_e32 v102, v102, v103, vcc
	v_pk_mul_f32 v[92:93], v[92:93], v[102:103] op_sel_hi:[1,0]
	v_lshl_add_u64 v[100:101], v[100:101], 0, v[114:115]
	v_mul_f32_e32 v103, 0xbfb8aa3b, v92
	v_exp_f32_e32 v103, v103
	global_store_dwordx4 v[100:101], v[96:99], off nt
	v_pk_mul_f32 v[94:95], v[94:95], v[102:103] op_sel_hi:[1,0]
	s_nop 0
	v_mul_f32_e32 v96, 0xbfb8aa3b, v93
	v_exp_f32_e32 v97, v96
	v_mul_f32_e32 v98, 0xbfb8aa3b, v94
; __device__ __forceinline__ float sigmoid_f(float x) { return __builtin_amdgcn_rcpf(1.0f + __builtin_amdgcn_exp2f(-x * LOG2E)); }
; __device__ __forceinline__ u32x4 pack8(const f32x4 a, const f32x4 b) { u32x4 w; w.x = cvt_pk_bf16(a[0], a[1]); w.y = cvt_pk_bf16(a[2], a[3]); w.z = cvt_pk_bf16(b[0], b[1]); w.w = cvt_pk_bf16(b[2], b[3]); return w; }
;     __device__ __forceinline__ void operator()(const Acc& acc, const Unit& u, int wr, int wc, int fr, int fq, const float (&sv8)[8]) const {
;     ...
;                 const int row = rowb + ai * 128 + m * 16;
;                 const float rs = rsqrtf(sv8[ai * 4 + m] * (1.0f / DM) + EPS);
;                 f32x4 h[2];
; #pragma unroll
;                 for (int n = 0; n < 2; ++n)
; #pragma unroll
;                     for (int j = 0; j < 4; ++j) { const float gv = acc[ai][0][m][n][j] * rs, uv = acc[ai][1][m][n][j] * rs; h[n][j] = gv * sigmoid_f(gv) * uv; }
;                 __builtin_nontemporal_store(pack8(h[0], h[1]), (u32x4*)(H + (size_t)row * FF + col0));
	v_mul_f32_e32 v99, 0xbfb8aa3b, v95
	v_exp_f32_e32 v98, v98
	v_exp_f32_e32 v99, v99
	v_add_f32_e32 v96, 1.0, v103
	v_add_f32_e32 v97, 1.0, v97
	v_rcp_f32_e32 v96, v96
	v_rcp_f32_e32 v97, v97
	v_add_f32_e32 v98, 1.0, v98
	v_add_f32_e32 v99, 1.0, v99
	v_rcp_f32_e32 v98, v98
	v_rcp_f32_e32 v99, v99
	v_pk_mul_f32 v[88:89], v[88:89], v[102:103] op_sel_hi:[1,0]
	v_pk_mul_f32 v[92:93], v[92:93], v[96:97]
	v_pk_mul_f32 v[84:85], v[84:85], v[102:103] op_sel_hi:[1,0]
	v_pk_mul_f32 v[88:89], v[88:89], v[92:93]
	v_pk_mul_f32 v[92:93], v[94:95], v[98:99]
	v_mul_f32_e32 v94, 0xbfb8aa3b, v84
	v_exp_f32_e32 v94, v94
	v_pk_mul_f32 v[90:91], v[90:91], v[102:103] op_sel_hi:[1,0]
	v_pk_mul_f32 v[86:87], v[86:87], v[102:103] op_sel_hi:[1,0]
	v_pk_mul_f32 v[90:91], v[90:91], v[92:93]
	v_mul_f32_e32 v92, 0xbfb8aa3b, v85
	v_exp_f32_e32 v93, v92
	v_add_f32_e32 v92, 1.0, v94
	v_mul_f32_e32 v94, 0xbfb8aa3b, v86
	v_mul_f32_e32 v95, 0xbfb8aa3b, v87
	v_exp_f32_e32 v94, v94
	v_exp_f32_e32 v95, v95
	v_add_f32_e32 v93, 1.0, v93
	v_rcp_f32_e32 v92, v92
	v_rcp_f32_e32 v93, v93
	v_add_f32_e32 v94, 1.0, v94
	v_add_f32_e32 v95, 1.0, v95
	v_rcp_f32_e32 v94, v94
	v_rcp_f32_e32 v95, v95
	v_pk_mul_f32 v[80:81], v[80:81], v[102:103] op_sel_hi:[1,0]
	v_pk_mul_f32 v[84:85], v[84:85], v[92:93]
	v_or_b32_e32 v92, 32, v210
	v_pk_mul_f32 v[84:85], v[80:81], v[84:85]
	v_pk_mul_f32 v[80:81], v[82:83], v[102:103] op_sel_hi:[1,0]
	v_pk_mul_f32 v[82:83], v[86:87], v[94:95]
	s_nop 0
	v_pk_mul_f32 v[86:87], v[80:81], v[82:83]
	v_cvt_pk_bf16_f32 v82, v84, v85
	v_fmamk_f32 v84, v232, 0x3a000000, v227
	v_mul_f32_e32 v85, 0x4b800000, v84
	v_cmp_gt_f32_e32 vcc, s54, v84
	v_cvt_pk_bf16_f32 v83, v86, v87
	v_cvt_pk_bf16_f32 v80, v88, v89
	v_cndmask_b32_e32 v84, v84, v85, vcc
	v_rsq_f32_e32 v86, v84
	v_mad_i64_i32 v[84:85], s[28:29], v92, s55, v[112:113]
	v_cvt_pk_bf16_f32 v81, v90, v91
	v_mul_f32_e32 v87, 0x45800000, v86
	v_cndmask_b32_e32 v86, v86, v87, vcc
	v_pk_mul_f32 v[76:77], v[76:77], v[86:87] op_sel_hi:[1,0]
	v_lshl_add_u64 v[84:85], v[84:85], 0, v[114:115]
	v_mul_f32_e32 v87, 0xbfb8aa3b, v76
	v_exp_f32_e32 v87, v87
	global_store_dwordx4 v[84:85], v[80:83], off nt
	v_pk_mul_f32 v[78:79], v[78:79], v[86:87] op_sel_hi:[1,0]
	s_nop 0
	v_mul_f32_e32 v80, 0xbfb8aa3b, v77
	v_exp_f32_e32 v81, v80
	v_mul_f32_e32 v82, 0xbfb8aa3b, v78
	v_mul_f32_e32 v83, 0xbfb8aa3b, v79
	v_exp_f32_e32 v82, v82
	v_exp_f32_e32 v83, v83
	v_add_f32_e32 v80, 1.0, v87
	v_add_f32_e32 v81, 1.0, v81
	v_rcp_f32_e32 v80, v80
	v_rcp_f32_e32 v81, v81
	v_add_f32_e32 v82, 1.0, v82
	v_add_f32_e32 v83, 1.0, v83
	v_rcp_f32_e32 v82, v82
	v_rcp_f32_e32 v83, v83
	v_pk_mul_f32 v[72:73], v[72:73], v[86:87] op_sel_hi:[1,0]
	v_pk_mul_f32 v[76:77], v[76:77], v[80:81]
	v_pk_mul_f32 v[68:69], v[68:69], v[86:87] op_sel_hi:[1,0]
	v_pk_mul_f32 v[72:73], v[72:73], v[76:77]
	v_pk_mul_f32 v[76:77], v[78:79], v[82:83]
	v_mul_f32_e32 v78, 0xbfb8aa3b, v68
	v_exp_f32_e32 v78, v78
	v_pk_mul_f32 v[74:75], v[74:75], v[86:87] op_sel_hi:[1,0]
	v_pk_mul_f32 v[70:71], v[70:71], v[86:87] op_sel_hi:[1,0]
	v_pk_mul_f32 v[74:75], v[74:75], v[76:77]
	v_mul_f32_e32 v76, 0xbfb8aa3b, v69
	v_exp_f32_e32 v77, v76
	v_add_f32_e32 v76, 1.0, v78
	v_mul_f32_e32 v78, 0xbfb8aa3b, v70
	v_mul_f32_e32 v79, 0xbfb8aa3b, v71
	v_exp_f32_e32 v78, v78
	v_exp_f32_e32 v79, v79
	v_add_f32_e32 v77, 1.0, v77
	v_rcp_f32_e32 v76, v76
	v_rcp_f32_e32 v77, v77
	v_add_f32_e32 v78, 1.0, v78
	v_add_f32_e32 v79, 1.0, v79
	v_rcp_f32_e32 v78, v78
	v_rcp_f32_e32 v79, v79
	v_pk_mul_f32 v[64:65], v[64:65], v[86:87] op_sel_hi:[1,0]
	v_pk_mul_f32 v[68:69], v[68:69], v[76:77]
	v_or_b32_e32 v76, 48, v210
	v_pk_mul_f32 v[68:69], v[64:65], v[68:69]
	v_pk_mul_f32 v[64:65], v[66:67], v[86:87] op_sel_hi:[1,0]
	v_pk_mul_f32 v[66:67], v[70:71], v[78:79]
	s_nop 0
	v_pk_mul_f32 v[70:71], v[64:65], v[66:67]
	v_cvt_pk_bf16_f32 v66, v68, v69
	v_fmamk_f32 v68, v231, 0x3a000000, v227
	v_mul_f32_e32 v69, 0x4b800000, v68
	v_cmp_gt_f32_e32 vcc, s54, v68
	v_cvt_pk_bf16_f32 v67, v70, v71
	v_cvt_pk_bf16_f32 v64, v72, v73
	v_cndmask_b32_e32 v68, v68, v69, vcc
	v_rsq_f32_e32 v70, v68
	v_mad_i64_i32 v[68:69], s[28:29], v76, s55, v[112:113]
	v_cvt_pk_bf16_f32 v65, v74, v75
	v_lshl_add_u64 v[68:69], v[68:69], 0, v[114:115]
	global_store_dwordx4 v[68:69], v[64:67], off nt
	s_nop 1
	v_mul_f32_e32 v64, 0x45800000, v70
	v_cndmask_b32_e32 v64, v70, v64, vcc
	v_pk_mul_f32 v[60:61], v[60:61], v[64:65] op_sel_hi:[1,0]
	v_add_u32_e32 v70, 0x80, v210
	v_mul_f32_e32 v65, 0xbfb8aa3b, v60
	v_exp_f32_e32 v65, v65
	v_mul_f32_e32 v66, 0xbfb8aa3b, v61
	v_exp_f32_e32 v67, v66
	v_add_f32_e32 v65, 1.0, v65
	v_rcp_f32_e32 v66, v65
	v_pk_mul_f32 v[56:57], v[56:57], v[64:65] op_sel_hi:[1,0]
	v_add_f32_e32 v65, 1.0, v67
	v_pk_mul_f32 v[62:63], v[62:63], v[64:65] op_sel_hi:[1,0]
	s_nop 0
	v_mul_f32_e32 v67, 0xbfb8aa3b, v62
	v_exp_f32_e32 v68, v67
	v_mul_f32_e32 v67, 0xbfb8aa3b, v63
	v_exp_f32_e32 v69, v67
	v_rcp_f32_e32 v67, v65
	v_add_f32_e32 v65, 1.0, v68
	v_rcp_f32_e32 v68, v65
	v_add_f32_e32 v65, 1.0, v69
	v_rcp_f32_e32 v69, v65
	v_pk_mul_f32 v[60:61], v[60:61], v[66:67]
	v_pk_mul_f32 v[52:53], v[52:53], v[64:65] op_sel_hi:[1,0]
	v_pk_mul_f32 v[56:57], v[56:57], v[60:61]
	v_pk_mul_f32 v[60:61], v[62:63], v[68:69]
	v_mul_f32_e32 v62, 0xbfb8aa3b, v52
	v_exp_f32_e32 v62, v62
	v_pk_mul_f32 v[58:59], v[58:59], v[64:65] op_sel_hi:[1,0]
	v_pk_mul_f32 v[54:55], v[54:55], v[64:65] op_sel_hi:[1,0]
	v_pk_mul_f32 v[58:59], v[58:59], v[60:61]
	v_mul_f32_e32 v60, 0xbfb8aa3b, v53
	v_exp_f32_e32 v61, v60
	v_add_f32_e32 v60, 1.0, v62
	v_mul_f32_e32 v62, 0xbfb8aa3b, v54
	v_mul_f32_e32 v63, 0xbfb8aa3b, v55
	v_exp_f32_e32 v62, v62
	v_exp_f32_e32 v63, v63
	v_add_f32_e32 v61, 1.0, v61
; __device__ __forceinline__ float sigmoid_f(float x) { return __builtin_amdgcn_rcpf(1.0f + __builtin_amdgcn_exp2f(-x * LOG2E)); }
; __device__ __forceinline__ u32x4 pack8(const f32x4 a, const f32x4 b) { u32x4 w; w.x = cvt_pk_bf16(a[0], a[1]); w.y = cvt_pk_bf16(a[2], a[3]); w.z = cvt_pk_bf16(b[0], b[1]); w.w = cvt_pk_bf16(b[2], b[3]); return w; }
;     __device__ __forceinline__ void operator()(const Acc& acc, const Unit& u, int wr, int wc, int fr, int fq, const float (&sv8)[8]) const {
;     ...
;             for (int m = 0; m < 4; ++m) {
;                 const int row = rowb + ai * 128 + m * 16;
;                 const float rs = rsqrtf(sv8[ai * 4 + m] * (1.0f / DM) + EPS);
;                 f32x4 h[2];
; #pragma unroll
;                 for (int n = 0; n < 2; ++n)
; #pragma unroll
;                     for (int j = 0; j < 4; ++j) { const float gv = acc[ai][0][m][n][j] * rs, uv = acc[ai][1][m][n][j] * rs; h[n][j] = gv * sigmoid_f(gv) * uv; }
;                 __builtin_nontemporal_store(pack8(h[0], h[1]), (u32x4*)(H + (size_t)row * FF + col0));
	v_rcp_f32_e32 v60, v60
	v_rcp_f32_e32 v61, v61
	v_add_f32_e32 v62, 1.0, v62
	v_add_f32_e32 v63, 1.0, v63
	v_rcp_f32_e32 v62, v62
	v_rcp_f32_e32 v63, v63
	v_pk_mul_f32 v[48:49], v[48:49], v[64:65] op_sel_hi:[1,0]
	v_pk_mul_f32 v[52:53], v[52:53], v[60:61]
	s_nop 0
	v_pk_mul_f32 v[52:53], v[48:49], v[52:53]
	v_pk_mul_f32 v[48:49], v[50:51], v[64:65] op_sel_hi:[1,0]
	v_pk_mul_f32 v[50:51], v[54:55], v[62:63]
	s_nop 0
	v_pk_mul_f32 v[54:55], v[48:49], v[50:51]
	v_cvt_pk_bf16_f32 v50, v52, v53
	v_fmamk_f32 v52, v230, 0x3a000000, v227
	v_mul_f32_e32 v53, 0x4b800000, v52
	v_cmp_gt_f32_e32 vcc, s54, v52
	v_cvt_pk_bf16_f32 v51, v54, v55
	v_cvt_pk_bf16_f32 v48, v56, v57
	v_cndmask_b32_e32 v52, v52, v53, vcc
	v_rsq_f32_e32 v54, v52
	v_mad_i64_i32 v[52:53], s[28:29], v70, s55, v[112:113]
	v_cvt_pk_bf16_f32 v49, v58, v59
	v_mul_f32_e32 v55, 0x45800000, v54
	v_cndmask_b32_e32 v54, v54, v55, vcc
	v_pk_mul_f32 v[44:45], v[44:45], v[54:55] op_sel_hi:[1,0]
	v_lshl_add_u64 v[52:53], v[52:53], 0, v[114:115]
	v_mul_f32_e32 v55, 0xbfb8aa3b, v44
	v_exp_f32_e32 v55, v55
	global_store_dwordx4 v[52:53], v[48:51], off nt
	v_pk_mul_f32 v[46:47], v[46:47], v[54:55] op_sel_hi:[1,0]
	s_nop 0
	v_mul_f32_e32 v48, 0xbfb8aa3b, v45
	v_exp_f32_e32 v49, v48
	v_mul_f32_e32 v50, 0xbfb8aa3b, v46
	v_mul_f32_e32 v51, 0xbfb8aa3b, v47
	v_exp_f32_e32 v50, v50
	v_exp_f32_e32 v51, v51
	v_add_f32_e32 v48, 1.0, v55
	v_add_f32_e32 v49, 1.0, v49
	v_rcp_f32_e32 v48, v48
	v_rcp_f32_e32 v49, v49
	v_add_f32_e32 v50, 1.0, v50
	v_add_f32_e32 v51, 1.0, v51
	v_rcp_f32_e32 v50, v50
	v_rcp_f32_e32 v51, v51
	v_pk_mul_f32 v[40:41], v[40:41], v[54:55] op_sel_hi:[1,0]
	v_pk_mul_f32 v[44:45], v[44:45], v[48:49]
	v_pk_mul_f32 v[36:37], v[36:37], v[54:55] op_sel_hi:[1,0]
	v_pk_mul_f32 v[40:41], v[40:41], v[44:45]
	v_pk_mul_f32 v[44:45], v[46:47], v[50:51]
	v_mul_f32_e32 v46, 0xbfb8aa3b, v36
	v_exp_f32_e32 v46, v46
	v_pk_mul_f32 v[42:43], v[42:43], v[54:55] op_sel_hi:[1,0]
	v_pk_mul_f32 v[38:39], v[38:39], v[54:55] op_sel_hi:[1,0]
	v_pk_mul_f32 v[42:43], v[42:43], v[44:45]
	v_mul_f32_e32 v44, 0xbfb8aa3b, v37
	v_exp_f32_e32 v45, v44
	v_add_f32_e32 v44, 1.0, v46
	v_mul_f32_e32 v46, 0xbfb8aa3b, v38
	v_mul_f32_e32 v47, 0xbfb8aa3b, v39
	v_exp_f32_e32 v46, v46
	v_exp_f32_e32 v47, v47
	v_add_f32_e32 v45, 1.0, v45
	v_rcp_f32_e32 v44, v44
	v_rcp_f32_e32 v45, v45
	v_add_f32_e32 v46, 1.0, v46
	v_add_f32_e32 v47, 1.0, v47
	v_rcp_f32_e32 v46, v46
	v_rcp_f32_e32 v47, v47
	v_pk_mul_f32 v[32:33], v[32:33], v[54:55] op_sel_hi:[1,0]
	v_pk_mul_f32 v[36:37], v[36:37], v[44:45]
	v_add_u32_e32 v44, 0x90, v210
	v_pk_mul_f32 v[36:37], v[32:33], v[36:37]
	v_pk_mul_f32 v[32:33], v[34:35], v[54:55] op_sel_hi:[1,0]
	v_pk_mul_f32 v[34:35], v[38:39], v[46:47]
	s_nop 0
	v_pk_mul_f32 v[38:39], v[32:33], v[34:35]
	v_cvt_pk_bf16_f32 v34, v36, v37
	v_fmamk_f32 v36, v229, 0x3a000000, v227
	v_mul_f32_e32 v37, 0x4b800000, v36
	v_cmp_gt_f32_e32 vcc, s54, v36
	v_cvt_pk_bf16_f32 v35, v38, v39
	v_cvt_pk_bf16_f32 v32, v40, v41
	v_cndmask_b32_e32 v36, v36, v37, vcc
	v_rsq_f32_e32 v38, v36
	v_mad_i64_i32 v[36:37], s[28:29], v44, s55, v[112:113]
	v_cvt_pk_bf16_f32 v33, v42, v43
	v_mul_f32_e32 v39, 0x45800000, v38
	v_cndmask_b32_e32 v38, v38, v39, vcc
	v_pk_mul_f32 v[28:29], v[28:29], v[38:39] op_sel_hi:[1,0]
	v_lshl_add_u64 v[36:37], v[36:37], 0, v[114:115]
	v_mul_f32_e32 v39, 0xbfb8aa3b, v28
	v_exp_f32_e32 v39, v39
	global_store_dwordx4 v[36:37], v[32:35], off nt
	v_pk_mul_f32 v[30:31], v[30:31], v[38:39] op_sel_hi:[1,0]
	s_nop 0
	v_mul_f32_e32 v32, 0xbfb8aa3b, v29
	v_exp_f32_e32 v33, v32
	v_mul_f32_e32 v34, 0xbfb8aa3b, v30
	v_mul_f32_e32 v35, 0xbfb8aa3b, v31
	v_exp_f32_e32 v34, v34
	v_exp_f32_e32 v35, v35
	v_add_f32_e32 v32, 1.0, v39
	v_add_f32_e32 v33, 1.0, v33
	v_rcp_f32_e32 v32, v32
	v_rcp_f32_e32 v33, v33
	v_add_f32_e32 v34, 1.0, v34
	v_add_f32_e32 v35, 1.0, v35
	v_rcp_f32_e32 v34, v34
	v_rcp_f32_e32 v35, v35
; __device__ __forceinline__ float sigmoid_f(float x) { return __builtin_amdgcn_rcpf(1.0f + __builtin_amdgcn_exp2f(-x * LOG2E)); }
; __device__ __forceinline__ u32x4 pack8(const f32x4 a, const f32x4 b) { u32x4 w; w.x = cvt_pk_bf16(a[0], a[1]); w.y = cvt_pk_bf16(a[2], a[3]); w.z = cvt_pk_bf16(b[0], b[1]); w.w = cvt_pk_bf16(b[2], b[3]); return w; }
; #define PG8_BAR __builtin_amdgcn_s_barrier()
;     ...
;         if (!has_next) break;
; #pragma unroll
;         for (int a = 0; a < 2; ++a)
; #pragma unroll
;             for (int b = 0; b < 2; ++b)
; #pragma unroll
;                 for (int m = 0; m < 4; ++m)
; #pragma unroll
;                     for (int n = 0; n < 2; ++n) acc[a][b][m][n] = (f32x4){0.f, 0.f, 0.f, 0.f};
;         cur = nxt; cA = nA; cB = nB; ++ui;
;         if constexpr (ALIGN_EPI) { if (wr == 1) PG8_BAR; }
;     __device__ __forceinline__ void operator()(const Acc& acc, const Unit& u, int wr, int wc, int fr, int fq, const float (&sv8)[8]) const {
;     ...
;                 const int row = rowb + ai * 128 + m * 16;
;                 const float rs = rsqrtf(sv8[ai * 4 + m] * (1.0f / DM) + EPS);
;                 f32x4 h[2];
; #pragma unroll
;                 for (int n = 0; n < 2; ++n)
; #pragma unroll
;                     for (int j = 0; j < 4; ++j) { const float gv = acc[ai][0][m][n][j] * rs, uv = acc[ai][1][m][n][j] * rs; h[n][j] = gv * sigmoid_f(gv) * uv; }
;                 __builtin_nontemporal_store(pack8(h[0], h[1]), (u32x4*)(H + (size_t)row * FF + col0));
	v_pk_mul_f32 v[24:25], v[24:25], v[38:39] op_sel_hi:[1,0]
	v_pk_mul_f32 v[28:29], v[28:29], v[32:33]
	v_pk_mul_f32 v[20:21], v[20:21], v[38:39] op_sel_hi:[1,0]
	v_pk_mul_f32 v[24:25], v[24:25], v[28:29]
	v_pk_mul_f32 v[28:29], v[30:31], v[34:35]
	v_mul_f32_e32 v30, 0xbfb8aa3b, v20
	v_exp_f32_e32 v30, v30
	v_pk_mul_f32 v[26:27], v[26:27], v[38:39] op_sel_hi:[1,0]
	v_pk_mul_f32 v[22:23], v[22:23], v[38:39] op_sel_hi:[1,0]
	v_pk_mul_f32 v[26:27], v[26:27], v[28:29]
	v_mul_f32_e32 v28, 0xbfb8aa3b, v21
	v_exp_f32_e32 v29, v28
	v_add_f32_e32 v28, 1.0, v30
	v_mul_f32_e32 v30, 0xbfb8aa3b, v22
	v_mul_f32_e32 v31, 0xbfb8aa3b, v23
	v_exp_f32_e32 v30, v30
	v_exp_f32_e32 v31, v31
	v_add_f32_e32 v29, 1.0, v29
	v_rcp_f32_e32 v28, v28
	v_rcp_f32_e32 v29, v29
	v_add_f32_e32 v30, 1.0, v30
	v_add_f32_e32 v31, 1.0, v31
	v_rcp_f32_e32 v30, v30
	v_rcp_f32_e32 v31, v31
	v_pk_mul_f32 v[16:17], v[16:17], v[38:39] op_sel_hi:[1,0]
	v_pk_mul_f32 v[20:21], v[20:21], v[28:29]
	v_add_u32_e32 v28, 0xa0, v210
	v_pk_mul_f32 v[20:21], v[16:17], v[20:21]
	v_pk_mul_f32 v[16:17], v[18:19], v[38:39] op_sel_hi:[1,0]
	v_pk_mul_f32 v[18:19], v[22:23], v[30:31]
	s_nop 0
	v_pk_mul_f32 v[22:23], v[16:17], v[18:19]
	v_cvt_pk_bf16_f32 v18, v20, v21
	v_fmamk_f32 v20, v228, 0x3a000000, v227
	v_mul_f32_e32 v21, 0x4b800000, v20
	v_cmp_gt_f32_e32 vcc, s54, v20
	v_cvt_pk_bf16_f32 v19, v22, v23
	v_cvt_pk_bf16_f32 v16, v24, v25
	v_cndmask_b32_e32 v20, v20, v21, vcc
	v_rsq_f32_e32 v22, v20
	v_mad_i64_i32 v[20:21], s[28:29], v28, s55, v[112:113]
	v_cvt_pk_bf16_f32 v17, v26, v27
	v_mul_f32_e32 v23, 0x45800000, v22
	v_cndmask_b32_e32 v22, v22, v23, vcc
	v_pk_mul_f32 v[12:13], v[12:13], v[22:23] op_sel_hi:[1,0]
	v_lshl_add_u64 v[20:21], v[20:21], 0, v[114:115]
	v_mul_f32_e32 v23, 0xbfb8aa3b, v12
	v_exp_f32_e32 v23, v23
	global_store_dwordx4 v[20:21], v[16:19], off nt
	s_andn2_b64 vcc, exec, s[8:9]
	s_mov_b64 s[8:9], -1
	v_mul_f32_e32 v16, 0xbfb8aa3b, v13
	v_pk_mul_f32 v[14:15], v[14:15], v[22:23] op_sel_hi:[1,0]
	v_exp_f32_e32 v17, v16
	v_mul_f32_e32 v18, 0xbfb8aa3b, v14
	v_mul_f32_e32 v19, 0xbfb8aa3b, v15
	v_exp_f32_e32 v18, v18
	v_exp_f32_e32 v19, v19
	v_add_f32_e32 v16, 1.0, v23
	v_add_f32_e32 v17, 1.0, v17
	v_rcp_f32_e32 v16, v16
	v_rcp_f32_e32 v17, v17
	v_add_f32_e32 v18, 1.0, v18
	v_add_f32_e32 v19, 1.0, v19
	v_rcp_f32_e32 v18, v18
	v_rcp_f32_e32 v19, v19
	v_pk_mul_f32 v[8:9], v[8:9], v[22:23] op_sel_hi:[1,0]
	v_pk_mul_f32 v[12:13], v[12:13], v[16:17]
	v_pk_mul_f32 v[4:5], v[4:5], v[22:23] op_sel_hi:[1,0]
	v_pk_mul_f32 v[8:9], v[8:9], v[12:13]
	v_pk_mul_f32 v[12:13], v[14:15], v[18:19]
	v_mul_f32_e32 v14, 0xbfb8aa3b, v4
	v_exp_f32_e32 v14, v14
	v_pk_mul_f32 v[10:11], v[10:11], v[22:23] op_sel_hi:[1,0]
	v_pk_mul_f32 v[6:7], v[6:7], v[22:23] op_sel_hi:[1,0]
	v_pk_mul_f32 v[10:11], v[10:11], v[12:13]
	v_mul_f32_e32 v12, 0xbfb8aa3b, v5
	v_exp_f32_e32 v13, v12
	v_add_f32_e32 v12, 1.0, v14
	v_mul_f32_e32 v14, 0xbfb8aa3b, v6
	v_mul_f32_e32 v15, 0xbfb8aa3b, v7
	v_exp_f32_e32 v14, v14
	v_exp_f32_e32 v15, v15
	v_add_f32_e32 v13, 1.0, v13
	v_rcp_f32_e32 v12, v12
	v_rcp_f32_e32 v13, v13
	v_add_f32_e32 v14, 1.0, v14
	v_add_f32_e32 v15, 1.0, v15
	v_rcp_f32_e32 v14, v14
	v_rcp_f32_e32 v15, v15
	v_pk_mul_f32 v[0:1], v[0:1], v[22:23] op_sel_hi:[1,0]
	v_pk_mul_f32 v[4:5], v[4:5], v[12:13]
	v_add_u32_e32 v12, 0xb0, v210
	v_pk_mul_f32 v[4:5], v[0:1], v[4:5]
	v_pk_mul_f32 v[0:1], v[2:3], v[22:23] op_sel_hi:[1,0]
	v_pk_mul_f32 v[2:3], v[6:7], v[14:15]
	s_nop 0
	v_pk_mul_f32 v[6:7], v[0:1], v[2:3]
	v_cvt_pk_bf16_f32 v2, v4, v5
	v_mad_i64_i32 v[4:5], s[28:29], v12, s55, v[112:113]
	v_cvt_pk_bf16_f32 v0, v8, v9
	v_cvt_pk_bf16_f32 v1, v10, v11
	v_cvt_pk_bf16_f32 v3, v6, v7
	v_lshl_add_u64 v[4:5], v[4:5], 0, v[114:115]
	global_store_dwordx4 v[4:5], v[0:3], off nt
	s_cbranch_vccnz .LBB0_143
	s_andn2_b64 vcc, exec, s[14:15]
	s_cbranch_vccnz .LBB0_142
	s_barrier
	s_branch .LBB0_142

; __device__ __forceinline__ u32x4 pack8(const f32x4 a, const f32x4 b) { u32x4 w; w.x = cvt_pk_bf16(a[0], a[1]); w.y = cvt_pk_bf16(a[2], a[3]); w.z = cvt_pk_bf16(b[0], b[1]); w.w = cvt_pk_bf16(b[2], b[3]); return w; }
;     __device__ __forceinline__ void operator()(const Acc& acc, const Unit& u, int wr, int wc, int fr, int fq, const float (&sv8)[8]) const {
;     ...
;                 const int row = rowb + ai * 128 + m * 16;
;                 const float rs = rsqrtf(sv8[ai * 4 + m] * (1.0f / DM) + EPS);
; #pragma unroll
;                 for (int bj = 0; bj < 2; ++bj) {
;                     const int cl = bj * 128 + wc * 32 + 8 * fq;
;                     const f32x4 v0 = acc[ai][bj][m][0] * rs, v1 = acc[ai][bj][m][1] * rs;
;                     if (u.pn < 4) *(u32x4*)(Q + (size_t)row * 1024 + u.pn * 256 + cl) = pack8(v0, v1);
;                     else if (u.pn == 4) *(u32x4*)(Kb + (size_t)row * 256 + cl) = pack8(v0, v1);
;                     else if (u.pn == 5) {
;                         const u32x4 w = pack8(v0, v1); bf16_t* p = VT + (size_t)cl * T + row;
;                         p[0] = (bf16_t)(w.x & 0xffff); p[(size_t)T] = (bf16_t)(w.x >> 16); p[(size_t)2 * T] = (bf16_t)(w.y & 0xffff); p[(size_t)3 * T] = (bf16_t)(w.y >> 16);
;                         p[(size_t)4 * T] = (bf16_t)(w.z & 0xffff); p[(size_t)5 * T] = (bf16_t)(w.z >> 16); p[(size_t)6 * T] = (bf16_t)(w.w & 0xffff); p[(size_t)7 * T] = (bf16_t)(w.w >> 16);
;                     } else {
;                         const int uc = (u.pn - 6) * 256 + cl, gi = uc >> 4, ch0 = uc & 15;
;                         *(u32x4*)(ACAT + ((size_t)gi * NCH + (row >> 4)) * 512 + (row & 15) * 16 + ch0) = pack8(v0, v1);
.LBB0_382:
	v_fmamk_f32 v129, v248, 0x3a000000, v240
	v_mul_f32_e32 v130, 0x4b800000, v129
	v_cmp_gt_f32_e32 vcc, s66, v129
	s_lshl_b32 s6, s6, 8
	s_add_i32 s6, s6, s49
	v_cndmask_b32_e32 v129, v129, v130, vcc
	v_rsq_f32_e32 v129, v129
	v_or_b32_e32 v128, s6, v193
	s_cmp_gt_i32 s12, 3
	s_cselect_b64 s[34:35], -1, 0
	v_mul_f32_e32 v130, 0x45800000, v129
	s_lshl_b32 s28, s12, 8
	v_cndmask_b32_e32 v132, v129, v130, vcc
	v_ashrrev_i32_e32 v129, 31, v128
	s_ashr_i32 s30, s6, 4
	s_add_i32 s21, s28, 0xfffffa00
	v_lshlrev_b64 v[130:131], 9, v[128:129]
	s_ashr_i32 s31, s30, 31
	v_pk_mul_f32 v[126:127], v[126:127], v[132:133] op_sel_hi:[1,0]
	v_pk_mul_f32 v[124:125], v[124:125], v[132:133] op_sel_hi:[1,0]
	v_pk_mul_f32 v[122:123], v[122:123], v[132:133] op_sel_hi:[1,0]
	v_pk_mul_f32 v[134:135], v[120:121], v[132:133] op_sel_hi:[1,0]
	s_mov_b64 s[6:7], -1
	s_and_b64 vcc, exec, s[34:35]
	s_cbranch_vccz .LBB0_392
	s_cmp_lt_i32 s12, 5
	s_cbranch_scc1 .LBB0_389
	s_cmp_lg_u32 s12, 5
	s_cbranch_scc0 .LBB0_386
	v_or_b32_e32 v120, s21, v204
	v_lshrrev_b32_e32 v133, 4, v120
	v_mov_b64_e32 v[120:121], s[30:31]
	v_mad_u64_u32 v[120:121], s[6:7], v133, s67, v[120:121]
	v_lshlrev_b64 v[120:121], 10, v[120:121]
	v_cvt_pk_bf16_f32 v136, v124, v125
	v_cvt_pk_bf16_f32 v137, v126, v127
	v_cvt_pk_bf16_f32 v138, v134, v135
	v_cvt_pk_bf16_f32 v139, v122, v123
	v_lshl_add_u64 v[120:121], v[208:209], 0, v[120:121]
	global_store_dwordx4 v[120:121], v[136:139], off
	s_mov_b64 s[6:7], 0

; __device__ __forceinline__ float sigmoid_f(float x) { return __builtin_amdgcn_rcpf(1.0f + __builtin_amdgcn_exp2f(-x * LOG2E)); }
; __device__ __forceinline__ u32x4 pack8(const f32x4 a, const f32x4 b) { u32x4 w; w.x = cvt_pk_bf16(a[0], a[1]); w.y = cvt_pk_bf16(a[2], a[3]); w.z = cvt_pk_bf16(b[0], b[1]); w.w = cvt_pk_bf16(b[2], b[3]); return w; }
;     __device__ __forceinline__ void operator()(const Acc& acc, const Unit& u, int wr, int wc, int fr, int fq, const float (&sv8)[8]) const {
;         const int col0 = u.pn * 128 + wc * 32 + 8 * fq, rowb = u.pm * 256 + wr * 64 + fr;
; #pragma unroll
;         for (int ai = 0; ai < 2; ++ai)
; #pragma unroll
;             for (int m = 0; m < 4; ++m) {
;                 const int row = rowb + ai * 128 + m * 16;
;                 const float rs = rsqrtf(sv8[ai * 4 + m] * (1.0f / DM) + EPS);
;                 f32x4 h[2];
; #pragma unroll
;                 for (int n = 0; n < 2; ++n)
; #pragma unroll
;                     for (int j = 0; j < 4; ++j) { const float gv = acc[ai][0][m][n][j] * rs, uv = acc[ai][1][m][n][j] * rs; h[n][j] = gv * sigmoid_f(gv) * uv; }
;                 __builtin_nontemporal_store(pack8(h[0], h[1]), (u32x4*)(H + (size_t)row * FF + col0));
.LBB0_1367:
	v_fmamk_f32 v128, v235, 0x3a000000, v226
	v_mul_f32_e32 v129, 0x4b800000, v128
	v_cmp_gt_f32_e32 vcc, s54, v128
	s_nop 1
	v_cndmask_b32_e32 v128, v128, v129, vcc
	v_rsq_f32_e32 v130, v128
	v_lshl_or_b32 v128, s56, 7, v222
	v_ashrrev_i32_e32 v129, 31, v128
	v_mul_f32_e32 v131, 0x45800000, v130
	v_cndmask_b32_e32 v130, v130, v131, vcc
	v_pk_mul_f32 v[124:125], v[124:125], v[130:131] op_sel_hi:[1,0]
	s_nop 0
	v_mul_f32_e32 v131, 0xbfb8aa3b, v124
	v_exp_f32_e32 v131, v131
	v_mul_f32_e32 v132, 0xbfb8aa3b, v125
	v_exp_f32_e32 v133, v132
	v_pk_mul_f32 v[120:121], v[120:121], v[130:131] op_sel_hi:[1,0]
	v_add_f32_e32 v131, 1.0, v131
	v_rcp_f32_e32 v132, v131
	v_add_f32_e32 v131, 1.0, v133
	v_pk_mul_f32 v[126:127], v[126:127], v[130:131] op_sel_hi:[1,0]
	s_nop 0
	v_mul_f32_e32 v133, 0xbfb8aa3b, v126
	v_exp_f32_e32 v134, v133
	v_mul_f32_e32 v133, 0xbfb8aa3b, v127
	v_exp_f32_e32 v135, v133
	v_rcp_f32_e32 v133, v131
	v_add_f32_e32 v131, 1.0, v134
	v_rcp_f32_e32 v134, v131
	v_add_f32_e32 v131, 1.0, v135
	v_rcp_f32_e32 v135, v131
	v_pk_mul_f32 v[124:125], v[124:125], v[132:133]
	v_pk_mul_f32 v[116:117], v[116:117], v[130:131] op_sel_hi:[1,0]
	v_pk_mul_f32 v[120:121], v[120:121], v[124:125]
	v_pk_mul_f32 v[124:125], v[126:127], v[134:135]
	v_mul_f32_e32 v126, 0xbfb8aa3b, v116
	v_exp_f32_e32 v126, v126
	v_pk_mul_f32 v[122:123], v[122:123], v[130:131] op_sel_hi:[1,0]
	v_pk_mul_f32 v[118:119], v[118:119], v[130:131] op_sel_hi:[1,0]
	v_pk_mul_f32 v[122:123], v[122:123], v[124:125]
	v_mul_f32_e32 v124, 0xbfb8aa3b, v117
	v_exp_f32_e32 v125, v124
	v_add_f32_e32 v124, 1.0, v126
	v_mul_f32_e32 v126, 0xbfb8aa3b, v118
	v_mul_f32_e32 v127, 0xbfb8aa3b, v119
	v_exp_f32_e32 v126, v126
	v_exp_f32_e32 v127, v127
	v_add_f32_e32 v125, 1.0, v125
	v_rcp_f32_e32 v124, v124
	v_rcp_f32_e32 v125, v125
	v_add_f32_e32 v126, 1.0, v126
	v_add_f32_e32 v127, 1.0, v127
	v_rcp_f32_e32 v126, v126
	v_rcp_f32_e32 v127, v127
	v_pk_mul_f32 v[112:113], v[112:113], v[130:131] op_sel_hi:[1,0]
	v_pk_mul_f32 v[116:117], v[116:117], v[124:125]
	v_pk_mul_f32 v[114:115], v[114:115], v[130:131] op_sel_hi:[1,0]
	v_pk_mul_f32 v[112:113], v[112:113], v[116:117]
	v_pk_mul_f32 v[116:117], v[118:119], v[126:127]
	v_cvt_pk_bf16_f32 v118, v112, v113
	v_pk_mul_f32 v[114:115], v[114:115], v[116:117]
	v_cvt_pk_bf16_f32 v117, v122, v123
	v_cvt_pk_bf16_f32 v119, v114, v115
	v_fmamk_f32 v114, v233, 0x3a000000, v226
	v_mul_f32_e32 v115, 0x4b800000, v114
	v_cmp_gt_f32_e32 vcc, s54, v114
	v_mov_b64_e32 v[112:113], s[94:95]
	v_cvt_pk_bf16_f32 v116, v120, v121
	v_cndmask_b32_e32 v114, v114, v115, vcc
	v_rsq_f32_e32 v122, v114
	v_mad_i64_i32 v[120:121], s[26:27], v208, s55, v[112:113]
	v_lshlrev_b64 v[114:115], 1, v[128:129]
	v_mul_f32_e32 v123, 0x45800000, v122
	v_cndmask_b32_e32 v122, v122, v123, vcc
	v_pk_mul_f32 v[108:109], v[108:109], v[122:123] op_sel_hi:[1,0]
	v_lshl_add_u64 v[120:121], v[120:121], 0, v[114:115]
	v_mul_f32_e32 v123, 0xbfb8aa3b, v108
	v_exp_f32_e32 v123, v123
	global_store_dwordx4 v[120:121], v[116:119], off nt
	v_pk_mul_f32 v[110:111], v[110:111], v[122:123] op_sel_hi:[1,0]
	s_nop 0
	v_mul_f32_e32 v116, 0xbfb8aa3b, v109
	v_exp_f32_e32 v117, v116
	v_mul_f32_e32 v118, 0xbfb8aa3b, v110
	v_mul_f32_e32 v119, 0xbfb8aa3b, v111
	v_exp_f32_e32 v118, v118
	v_exp_f32_e32 v119, v119
	v_add_f32_e32 v116, 1.0, v123
	v_add_f32_e32 v117, 1.0, v117
	v_rcp_f32_e32 v116, v116
	v_rcp_f32_e32 v117, v117
	v_add_f32_e32 v118, 1.0, v118
	v_add_f32_e32 v119, 1.0, v119
	v_rcp_f32_e32 v118, v118
	v_rcp_f32_e32 v119, v119
	v_pk_mul_f32 v[104:105], v[104:105], v[122:123] op_sel_hi:[1,0]
	v_pk_mul_f32 v[108:109], v[108:109], v[116:117]
	v_pk_mul_f32 v[100:101], v[100:101], v[122:123] op_sel_hi:[1,0]
	v_pk_mul_f32 v[104:105], v[104:105], v[108:109]
	v_pk_mul_f32 v[108:109], v[110:111], v[118:119]
	v_mul_f32_e32 v110, 0xbfb8aa3b, v100
	v_exp_f32_e32 v110, v110
	v_pk_mul_f32 v[106:107], v[106:107], v[122:123] op_sel_hi:[1,0]
	v_pk_mul_f32 v[102:103], v[102:103], v[122:123] op_sel_hi:[1,0]
	v_pk_mul_f32 v[106:107], v[106:107], v[108:109]
	v_mul_f32_e32 v108, 0xbfb8aa3b, v101
	v_exp_f32_e32 v109, v108
	v_add_f32_e32 v108, 1.0, v110
	v_mul_f32_e32 v110, 0xbfb8aa3b, v102
	v_mul_f32_e32 v111, 0xbfb8aa3b, v103
	v_exp_f32_e32 v110, v110
	v_exp_f32_e32 v111, v111
	v_add_f32_e32 v109, 1.0, v109
	v_rcp_f32_e32 v108, v108
	v_rcp_f32_e32 v109, v109
	v_add_f32_e32 v110, 1.0, v110
	v_add_f32_e32 v111, 1.0, v111
	v_rcp_f32_e32 v110, v110
	v_rcp_f32_e32 v111, v111
	v_pk_mul_f32 v[96:97], v[96:97], v[122:123] op_sel_hi:[1,0]
	v_pk_mul_f32 v[100:101], v[100:101], v[108:109]
	v_or_b32_e32 v108, 16, v208
	v_pk_mul_f32 v[100:101], v[96:97], v[100:101]
	v_pk_mul_f32 v[96:97], v[98:99], v[122:123] op_sel_hi:[1,0]
	v_pk_mul_f32 v[98:99], v[102:103], v[110:111]
	s_nop 0
	v_pk_mul_f32 v[102:103], v[96:97], v[98:99]
	v_cvt_pk_bf16_f32 v98, v100, v101
	v_fmamk_f32 v100, v232, 0x3a000000, v226
	v_mul_f32_e32 v101, 0x4b800000, v100
	v_cmp_gt_f32_e32 vcc, s54, v100
	v_cvt_pk_bf16_f32 v99, v102, v103
	v_cvt_pk_bf16_f32 v96, v104, v105
	v_cndmask_b32_e32 v100, v100, v101, vcc
	v_rsq_f32_e32 v102, v100
	v_mad_i64_i32 v[100:101], s[26:27], v108, s55, v[112:113]
	v_cvt_pk_bf16_f32 v97, v106, v107
	v_mul_f32_e32 v103, 0x45800000, v102
	v_cndmask_b32_e32 v102, v102, v103, vcc
	v_pk_mul_f32 v[92:93], v[92:93], v[102:103] op_sel_hi:[1,0]
	v_lshl_add_u64 v[100:101], v[100:101], 0, v[114:115]
	v_mul_f32_e32 v103, 0xbfb8aa3b, v92
	v_exp_f32_e32 v103, v103
	global_store_dwordx4 v[100:101], v[96:99], off nt
	v_pk_mul_f32 v[94:95], v[94:95], v[102:103] op_sel_hi:[1,0]
	s_nop 0
	v_mul_f32_e32 v96, 0xbfb8aa3b, v93
	v_exp_f32_e32 v97, v96
	v_mul_f32_e32 v98, 0xbfb8aa3b, v94
; __device__ __forceinline__ float sigmoid_f(float x) { return __builtin_amdgcn_rcpf(1.0f + __builtin_amdgcn_exp2f(-x * LOG2E)); }
; __device__ __forceinline__ u32x4 pack8(const f32x4 a, const f32x4 b) { u32x4 w; w.x = cvt_pk_bf16(a[0], a[1]); w.y = cvt_pk_bf16(a[2], a[3]); w.z = cvt_pk_bf16(b[0], b[1]); w.w = cvt_pk_bf16(b[2], b[3]); return w; }
;     __device__ __forceinline__ void operator()(const Acc& acc, const Unit& u, int wr, int wc, int fr, int fq, const float (&sv8)[8]) const {
;     ...
;             for (int m = 0; m < 4; ++m) {
;                 const int row = rowb + ai * 128 + m * 16;
;                 const float rs = rsqrtf(sv8[ai * 4 + m] * (1.0f / DM) + EPS);
;                 f32x4 h[2];
; #pragma unroll
;                 for (int n = 0; n < 2; ++n)
; #pragma unroll
;                     for (int j = 0; j < 4; ++j) { const float gv = acc[ai][0][m][n][j] * rs, uv = acc[ai][1][m][n][j] * rs; h[n][j] = gv * sigmoid_f(gv) * uv; }
;                 __builtin_nontemporal_store(pack8(h[0], h[1]), (u32x4*)(H + (size_t)row * FF + col0));
	v_mul_f32_e32 v99, 0xbfb8aa3b, v95
	v_exp_f32_e32 v98, v98
	v_exp_f32_e32 v99, v99
	v_add_f32_e32 v96, 1.0, v103
	v_add_f32_e32 v97, 1.0, v97
	v_rcp_f32_e32 v96, v96
	v_rcp_f32_e32 v97, v97
	v_add_f32_e32 v98, 1.0, v98
	v_add_f32_e32 v99, 1.0, v99
	v_rcp_f32_e32 v98, v98
	v_rcp_f32_e32 v99, v99
	v_pk_mul_f32 v[88:89], v[88:89], v[102:103] op_sel_hi:[1,0]
	v_pk_mul_f32 v[92:93], v[92:93], v[96:97]
	v_pk_mul_f32 v[84:85], v[84:85], v[102:103] op_sel_hi:[1,0]
	v_pk_mul_f32 v[88:89], v[88:89], v[92:93]
	v_pk_mul_f32 v[92:93], v[94:95], v[98:99]
	v_mul_f32_e32 v94, 0xbfb8aa3b, v84
	v_exp_f32_e32 v94, v94
	v_pk_mul_f32 v[90:91], v[90:91], v[102:103] op_sel_hi:[1,0]
	v_pk_mul_f32 v[86:87], v[86:87], v[102:103] op_sel_hi:[1,0]
	v_pk_mul_f32 v[90:91], v[90:91], v[92:93]
	v_mul_f32_e32 v92, 0xbfb8aa3b, v85
	v_exp_f32_e32 v93, v92
	v_add_f32_e32 v92, 1.0, v94
	v_mul_f32_e32 v94, 0xbfb8aa3b, v86
	v_mul_f32_e32 v95, 0xbfb8aa3b, v87
	v_exp_f32_e32 v94, v94
	v_exp_f32_e32 v95, v95
	v_add_f32_e32 v93, 1.0, v93
	v_rcp_f32_e32 v92, v92
	v_rcp_f32_e32 v93, v93
	v_add_f32_e32 v94, 1.0, v94
	v_add_f32_e32 v95, 1.0, v95
	v_rcp_f32_e32 v94, v94
	v_rcp_f32_e32 v95, v95
	v_pk_mul_f32 v[80:81], v[80:81], v[102:103] op_sel_hi:[1,0]
	v_pk_mul_f32 v[84:85], v[84:85], v[92:93]
	v_or_b32_e32 v92, 32, v208
	v_pk_mul_f32 v[84:85], v[80:81], v[84:85]
	v_pk_mul_f32 v[80:81], v[82:83], v[102:103] op_sel_hi:[1,0]
	v_pk_mul_f32 v[82:83], v[86:87], v[94:95]
	s_nop 0
	v_pk_mul_f32 v[86:87], v[80:81], v[82:83]
	v_cvt_pk_bf16_f32 v82, v84, v85
	v_fmamk_f32 v84, v231, 0x3a000000, v226
	v_mul_f32_e32 v85, 0x4b800000, v84
	v_cmp_gt_f32_e32 vcc, s54, v84
	v_cvt_pk_bf16_f32 v83, v86, v87
	v_cvt_pk_bf16_f32 v80, v88, v89
	v_cndmask_b32_e32 v84, v84, v85, vcc
	v_rsq_f32_e32 v86, v84
	v_mad_i64_i32 v[84:85], s[26:27], v92, s55, v[112:113]
	v_cvt_pk_bf16_f32 v81, v90, v91
	v_mul_f32_e32 v87, 0x45800000, v86
	v_cndmask_b32_e32 v86, v86, v87, vcc
	v_pk_mul_f32 v[76:77], v[76:77], v[86:87] op_sel_hi:[1,0]
	v_lshl_add_u64 v[84:85], v[84:85], 0, v[114:115]
	v_mul_f32_e32 v87, 0xbfb8aa3b, v76
	v_exp_f32_e32 v87, v87
	global_store_dwordx4 v[84:85], v[80:83], off nt
	v_pk_mul_f32 v[78:79], v[78:79], v[86:87] op_sel_hi:[1,0]
	s_nop 0
	v_mul_f32_e32 v80, 0xbfb8aa3b, v77
	v_exp_f32_e32 v81, v80
	v_mul_f32_e32 v82, 0xbfb8aa3b, v78
	v_mul_f32_e32 v83, 0xbfb8aa3b, v79
	v_exp_f32_e32 v82, v82
	v_exp_f32_e32 v83, v83
	v_add_f32_e32 v80, 1.0, v87
	v_add_f32_e32 v81, 1.0, v81
	v_rcp_f32_e32 v80, v80
	v_rcp_f32_e32 v81, v81
	v_add_f32_e32 v82, 1.0, v82
	v_add_f32_e32 v83, 1.0, v83
	v_rcp_f32_e32 v82, v82
	v_rcp_f32_e32 v83, v83
	v_pk_mul_f32 v[72:73], v[72:73], v[86:87] op_sel_hi:[1,0]
	v_pk_mul_f32 v[76:77], v[76:77], v[80:81]
	v_pk_mul_f32 v[68:69], v[68:69], v[86:87] op_sel_hi:[1,0]
	v_pk_mul_f32 v[72:73], v[72:73], v[76:77]
	v_pk_mul_f32 v[76:77], v[78:79], v[82:83]
	v_mul_f32_e32 v78, 0xbfb8aa3b, v68
	v_exp_f32_e32 v78, v78
	v_pk_mul_f32 v[74:75], v[74:75], v[86:87] op_sel_hi:[1,0]
	v_pk_mul_f32 v[70:71], v[70:71], v[86:87] op_sel_hi:[1,0]
	v_pk_mul_f32 v[74:75], v[74:75], v[76:77]
	v_mul_f32_e32 v76, 0xbfb8aa3b, v69
	v_exp_f32_e32 v77, v76
	v_add_f32_e32 v76, 1.0, v78
	v_mul_f32_e32 v78, 0xbfb8aa3b, v70
	v_mul_f32_e32 v79, 0xbfb8aa3b, v71
	v_exp_f32_e32 v78, v78
	v_exp_f32_e32 v79, v79
	v_add_f32_e32 v77, 1.0, v77
	v_rcp_f32_e32 v76, v76
	v_rcp_f32_e32 v77, v77
	v_add_f32_e32 v78, 1.0, v78
	v_add_f32_e32 v79, 1.0, v79
	v_rcp_f32_e32 v78, v78
	v_rcp_f32_e32 v79, v79
	v_pk_mul_f32 v[64:65], v[64:65], v[86:87] op_sel_hi:[1,0]
	v_pk_mul_f32 v[68:69], v[68:69], v[76:77]
	v_or_b32_e32 v76, 48, v208
	v_pk_mul_f32 v[68:69], v[64:65], v[68:69]
	v_pk_mul_f32 v[64:65], v[66:67], v[86:87] op_sel_hi:[1,0]
	v_pk_mul_f32 v[66:67], v[70:71], v[78:79]
	s_nop 0
	v_pk_mul_f32 v[70:71], v[64:65], v[66:67]
	v_cvt_pk_bf16_f32 v66, v68, v69
	v_fmamk_f32 v68, v230, 0x3a000000, v226
	v_mul_f32_e32 v69, 0x4b800000, v68
	v_cmp_gt_f32_e32 vcc, s54, v68
	v_cvt_pk_bf16_f32 v67, v70, v71
	v_cvt_pk_bf16_f32 v64, v72, v73
	v_cndmask_b32_e32 v68, v68, v69, vcc
	v_rsq_f32_e32 v70, v68
	v_mad_i64_i32 v[68:69], s[26:27], v76, s55, v[112:113]
	v_cvt_pk_bf16_f32 v65, v74, v75
	v_lshl_add_u64 v[68:69], v[68:69], 0, v[114:115]
	global_store_dwordx4 v[68:69], v[64:67], off nt
	s_nop 1
	v_mul_f32_e32 v64, 0x45800000, v70
	v_cndmask_b32_e32 v64, v70, v64, vcc
	v_pk_mul_f32 v[60:61], v[60:61], v[64:65] op_sel_hi:[1,0]
	v_add_u32_e32 v70, 0x80, v208
	v_mul_f32_e32 v65, 0xbfb8aa3b, v60
	v_exp_f32_e32 v65, v65
	v_mul_f32_e32 v66, 0xbfb8aa3b, v61
	v_exp_f32_e32 v67, v66
	v_add_f32_e32 v65, 1.0, v65
	v_rcp_f32_e32 v66, v65
	v_pk_mul_f32 v[56:57], v[56:57], v[64:65] op_sel_hi:[1,0]
	v_add_f32_e32 v65, 1.0, v67
	v_pk_mul_f32 v[62:63], v[62:63], v[64:65] op_sel_hi:[1,0]
	s_nop 0
	v_mul_f32_e32 v67, 0xbfb8aa3b, v62
	v_exp_f32_e32 v68, v67
	v_mul_f32_e32 v67, 0xbfb8aa3b, v63
	v_exp_f32_e32 v69, v67
	v_rcp_f32_e32 v67, v65
	v_add_f32_e32 v65, 1.0, v68
	v_rcp_f32_e32 v68, v65
	v_add_f32_e32 v65, 1.0, v69
	v_rcp_f32_e32 v69, v65
	v_pk_mul_f32 v[60:61], v[60:61], v[66:67]
	v_pk_mul_f32 v[52:53], v[52:53], v[64:65] op_sel_hi:[1,0]
	v_pk_mul_f32 v[56:57], v[56:57], v[60:61]
	v_pk_mul_f32 v[60:61], v[62:63], v[68:69]
	v_mul_f32_e32 v62, 0xbfb8aa3b, v52
	v_exp_f32_e32 v62, v62
	v_pk_mul_f32 v[58:59], v[58:59], v[64:65] op_sel_hi:[1,0]
	v_pk_mul_f32 v[54:55], v[54:55], v[64:65] op_sel_hi:[1,0]
	v_pk_mul_f32 v[58:59], v[58:59], v[60:61]
	v_mul_f32_e32 v60, 0xbfb8aa3b, v53
	v_exp_f32_e32 v61, v60
	v_add_f32_e32 v60, 1.0, v62
	v_mul_f32_e32 v62, 0xbfb8aa3b, v54
	v_mul_f32_e32 v63, 0xbfb8aa3b, v55
	v_exp_f32_e32 v62, v62
	v_exp_f32_e32 v63, v63
	v_add_f32_e32 v61, 1.0, v61
; __device__ __forceinline__ float sigmoid_f(float x) { return __builtin_amdgcn_rcpf(1.0f + __builtin_amdgcn_exp2f(-x * LOG2E)); }
; __device__ __forceinline__ u32x4 pack8(const f32x4 a, const f32x4 b) { u32x4 w; w.x = cvt_pk_bf16(a[0], a[1]); w.y = cvt_pk_bf16(a[2], a[3]); w.z = cvt_pk_bf16(b[0], b[1]); w.w = cvt_pk_bf16(b[2], b[3]); return w; }
;     __device__ __forceinline__ void operator()(const Acc& acc, const Unit& u, int wr, int wc, int fr, int fq, const float (&sv8)[8]) const {
;     ...
;             for (int m = 0; m < 4; ++m) {
;                 const int row = rowb + ai * 128 + m * 16;
;                 const float rs = rsqrtf(sv8[ai * 4 + m] * (1.0f / DM) + EPS);
;                 f32x4 h[2];
; #pragma unroll
;                 for (int n = 0; n < 2; ++n)
; #pragma unroll
;                     for (int j = 0; j < 4; ++j) { const float gv = acc[ai][0][m][n][j] * rs, uv = acc[ai][1][m][n][j] * rs; h[n][j] = gv * sigmoid_f(gv) * uv; }
;                 __builtin_nontemporal_store(pack8(h[0], h[1]), (u32x4*)(H + (size_t)row * FF + col0));
	v_rcp_f32_e32 v60, v60
	v_rcp_f32_e32 v61, v61
	v_add_f32_e32 v62, 1.0, v62
	v_add_f32_e32 v63, 1.0, v63
	v_rcp_f32_e32 v62, v62
	v_rcp_f32_e32 v63, v63
	v_pk_mul_f32 v[48:49], v[48:49], v[64:65] op_sel_hi:[1,0]
	v_pk_mul_f32 v[52:53], v[52:53], v[60:61]
	s_nop 0
	v_pk_mul_f32 v[52:53], v[48:49], v[52:53]
	v_pk_mul_f32 v[48:49], v[50:51], v[64:65] op_sel_hi:[1,0]
	v_pk_mul_f32 v[50:51], v[54:55], v[62:63]
	s_nop 0
	v_pk_mul_f32 v[54:55], v[48:49], v[50:51]
	v_cvt_pk_bf16_f32 v50, v52, v53
	v_fmamk_f32 v52, v229, 0x3a000000, v226
	v_mul_f32_e32 v53, 0x4b800000, v52
	v_cmp_gt_f32_e32 vcc, s54, v52
	v_cvt_pk_bf16_f32 v51, v54, v55
	v_cvt_pk_bf16_f32 v48, v56, v57
	v_cndmask_b32_e32 v52, v52, v53, vcc
	v_rsq_f32_e32 v54, v52
	v_mad_i64_i32 v[52:53], s[26:27], v70, s55, v[112:113]
	v_cvt_pk_bf16_f32 v49, v58, v59
	v_mul_f32_e32 v55, 0x45800000, v54
	v_cndmask_b32_e32 v54, v54, v55, vcc
	v_pk_mul_f32 v[44:45], v[44:45], v[54:55] op_sel_hi:[1,0]
	v_lshl_add_u64 v[52:53], v[52:53], 0, v[114:115]
	v_mul_f32_e32 v55, 0xbfb8aa3b, v44
	v_exp_f32_e32 v55, v55
	global_store_dwordx4 v[52:53], v[48:51], off nt
	v_pk_mul_f32 v[46:47], v[46:47], v[54:55] op_sel_hi:[1,0]
	s_nop 0
	v_mul_f32_e32 v48, 0xbfb8aa3b, v45
	v_exp_f32_e32 v49, v48
	v_mul_f32_e32 v50, 0xbfb8aa3b, v46
	v_mul_f32_e32 v51, 0xbfb8aa3b, v47
	v_exp_f32_e32 v50, v50
	v_exp_f32_e32 v51, v51
	v_add_f32_e32 v48, 1.0, v55
	v_add_f32_e32 v49, 1.0, v49
	v_rcp_f32_e32 v48, v48
	v_rcp_f32_e32 v49, v49
	v_add_f32_e32 v50, 1.0, v50
	v_add_f32_e32 v51, 1.0, v51
	v_rcp_f32_e32 v50, v50
	v_rcp_f32_e32 v51, v51
	v_pk_mul_f32 v[40:41], v[40:41], v[54:55] op_sel_hi:[1,0]
	v_pk_mul_f32 v[44:45], v[44:45], v[48:49]
	v_pk_mul_f32 v[36:37], v[36:37], v[54:55] op_sel_hi:[1,0]
	v_pk_mul_f32 v[40:41], v[40:41], v[44:45]
	v_pk_mul_f32 v[44:45], v[46:47], v[50:51]
	v_mul_f32_e32 v46, 0xbfb8aa3b, v36
	v_exp_f32_e32 v46, v46
	v_pk_mul_f32 v[42:43], v[42:43], v[54:55] op_sel_hi:[1,0]
	v_pk_mul_f32 v[38:39], v[38:39], v[54:55] op_sel_hi:[1,0]
	v_pk_mul_f32 v[42:43], v[42:43], v[44:45]
	v_mul_f32_e32 v44, 0xbfb8aa3b, v37
	v_exp_f32_e32 v45, v44
	v_add_f32_e32 v44, 1.0, v46
	v_mul_f32_e32 v46, 0xbfb8aa3b, v38
	v_mul_f32_e32 v47, 0xbfb8aa3b, v39
	v_exp_f32_e32 v46, v46
	v_exp_f32_e32 v47, v47
	v_add_f32_e32 v45, 1.0, v45
	v_rcp_f32_e32 v44, v44
	v_rcp_f32_e32 v45, v45
	v_add_f32_e32 v46, 1.0, v46
	v_add_f32_e32 v47, 1.0, v47
	v_rcp_f32_e32 v46, v46
	v_rcp_f32_e32 v47, v47
	v_pk_mul_f32 v[32:33], v[32:33], v[54:55] op_sel_hi:[1,0]
	v_pk_mul_f32 v[36:37], v[36:37], v[44:45]
	v_add_u32_e32 v44, 0x90, v208
	v_pk_mul_f32 v[36:37], v[32:33], v[36:37]
	v_pk_mul_f32 v[32:33], v[34:35], v[54:55] op_sel_hi:[1,0]
	v_pk_mul_f32 v[34:35], v[38:39], v[46:47]
	s_nop 0
	v_pk_mul_f32 v[38:39], v[32:33], v[34:35]
	v_cvt_pk_bf16_f32 v34, v36, v37
	v_fmamk_f32 v36, v228, 0x3a000000, v226
	v_mul_f32_e32 v37, 0x4b800000, v36
	v_cmp_gt_f32_e32 vcc, s54, v36
	v_cvt_pk_bf16_f32 v35, v38, v39
	v_cvt_pk_bf16_f32 v32, v40, v41
	v_cndmask_b32_e32 v36, v36, v37, vcc
	v_rsq_f32_e32 v38, v36
	v_mad_i64_i32 v[36:37], s[26:27], v44, s55, v[112:113]
	v_cvt_pk_bf16_f32 v33, v42, v43
	v_mul_f32_e32 v39, 0x45800000, v38
	v_cndmask_b32_e32 v38, v38, v39, vcc
	v_pk_mul_f32 v[28:29], v[28:29], v[38:39] op_sel_hi:[1,0]
	v_lshl_add_u64 v[36:37], v[36:37], 0, v[114:115]
	v_mul_f32_e32 v39, 0xbfb8aa3b, v28
	v_exp_f32_e32 v39, v39
	global_store_dwordx4 v[36:37], v[32:35], off nt
	v_pk_mul_f32 v[30:31], v[30:31], v[38:39] op_sel_hi:[1,0]
	s_nop 0
	v_mul_f32_e32 v32, 0xbfb8aa3b, v29
	v_exp_f32_e32 v33, v32
	v_mul_f32_e32 v34, 0xbfb8aa3b, v30
	v_mul_f32_e32 v35, 0xbfb8aa3b, v31
	v_exp_f32_e32 v34, v34
	v_exp_f32_e32 v35, v35
	v_add_f32_e32 v32, 1.0, v39
	v_add_f32_e32 v33, 1.0, v33
	v_rcp_f32_e32 v32, v32
	v_rcp_f32_e32 v33, v33
	v_add_f32_e32 v34, 1.0, v34
	v_add_f32_e32 v35, 1.0, v35
	v_rcp_f32_e32 v34, v34
	v_rcp_f32_e32 v35, v35
; __device__ __forceinline__ float sigmoid_f(float x) { return __builtin_amdgcn_rcpf(1.0f + __builtin_amdgcn_exp2f(-x * LOG2E)); }
; __device__ __forceinline__ u32x4 pack8(const f32x4 a, const f32x4 b) { u32x4 w; w.x = cvt_pk_bf16(a[0], a[1]); w.y = cvt_pk_bf16(a[2], a[3]); w.z = cvt_pk_bf16(b[0], b[1]); w.w = cvt_pk_bf16(b[2], b[3]); return w; }
; #define PG8_BAR __builtin_amdgcn_s_barrier()
;     ...
;         if (!has_next) break;
; #pragma unroll
;         for (int a = 0; a < 2; ++a)
; #pragma unroll
;             for (int b = 0; b < 2; ++b)
; #pragma unroll
;                 for (int m = 0; m < 4; ++m)
; #pragma unroll
;                     for (int n = 0; n < 2; ++n) acc[a][b][m][n] = (f32x4){0.f, 0.f, 0.f, 0.f};
;         cur = nxt; cA = nA; cB = nB; ++ui;
;         if constexpr (ALIGN_EPI) { if (wr == 1) PG8_BAR; }
;     __device__ __forceinline__ void operator()(const Acc& acc, const Unit& u, int wr, int wc, int fr, int fq, const float (&sv8)[8]) const {
;     ...
;             for (int m = 0; m < 4; ++m) {
;                 const int row = rowb + ai * 128 + m * 16;
;                 const float rs = rsqrtf(sv8[ai * 4 + m] * (1.0f / DM) + EPS);
;                 f32x4 h[2];
; #pragma unroll
;                 for (int n = 0; n < 2; ++n)
; #pragma unroll
;                     for (int j = 0; j < 4; ++j) { const float gv = acc[ai][0][m][n][j] * rs, uv = acc[ai][1][m][n][j] * rs; h[n][j] = gv * sigmoid_f(gv) * uv; }
;                 __builtin_nontemporal_store(pack8(h[0], h[1]), (u32x4*)(H + (size_t)row * FF + col0));
	v_pk_mul_f32 v[24:25], v[24:25], v[38:39] op_sel_hi:[1,0]
	v_pk_mul_f32 v[28:29], v[28:29], v[32:33]
	v_pk_mul_f32 v[20:21], v[20:21], v[38:39] op_sel_hi:[1,0]
	v_pk_mul_f32 v[24:25], v[24:25], v[28:29]
	v_pk_mul_f32 v[28:29], v[30:31], v[34:35]
	v_mul_f32_e32 v30, 0xbfb8aa3b, v20
	v_exp_f32_e32 v30, v30
	v_pk_mul_f32 v[26:27], v[26:27], v[38:39] op_sel_hi:[1,0]
	v_pk_mul_f32 v[22:23], v[22:23], v[38:39] op_sel_hi:[1,0]
	v_pk_mul_f32 v[26:27], v[26:27], v[28:29]
	v_mul_f32_e32 v28, 0xbfb8aa3b, v21
	v_exp_f32_e32 v29, v28
	v_add_f32_e32 v28, 1.0, v30
	v_mul_f32_e32 v30, 0xbfb8aa3b, v22
	v_mul_f32_e32 v31, 0xbfb8aa3b, v23
	v_exp_f32_e32 v30, v30
	v_exp_f32_e32 v31, v31
	v_add_f32_e32 v29, 1.0, v29
	v_rcp_f32_e32 v28, v28
	v_rcp_f32_e32 v29, v29
	v_add_f32_e32 v30, 1.0, v30
	v_add_f32_e32 v31, 1.0, v31
	v_rcp_f32_e32 v30, v30
	v_rcp_f32_e32 v31, v31
	v_pk_mul_f32 v[16:17], v[16:17], v[38:39] op_sel_hi:[1,0]
	v_pk_mul_f32 v[20:21], v[20:21], v[28:29]
	v_add_u32_e32 v28, 0xa0, v208
	v_pk_mul_f32 v[20:21], v[16:17], v[20:21]
	v_pk_mul_f32 v[16:17], v[18:19], v[38:39] op_sel_hi:[1,0]
	v_pk_mul_f32 v[18:19], v[22:23], v[30:31]
	s_nop 0
	v_pk_mul_f32 v[22:23], v[16:17], v[18:19]
	v_cvt_pk_bf16_f32 v18, v20, v21
	v_fmamk_f32 v20, v227, 0x3a000000, v226
	v_mul_f32_e32 v21, 0x4b800000, v20
	v_cmp_gt_f32_e32 vcc, s54, v20
	v_cvt_pk_bf16_f32 v19, v22, v23
	v_cvt_pk_bf16_f32 v16, v24, v25
	v_cndmask_b32_e32 v20, v20, v21, vcc
	v_rsq_f32_e32 v22, v20
	v_mad_i64_i32 v[20:21], s[26:27], v28, s55, v[112:113]
	v_cvt_pk_bf16_f32 v17, v26, v27
	v_mul_f32_e32 v23, 0x45800000, v22
	v_cndmask_b32_e32 v22, v22, v23, vcc
	v_pk_mul_f32 v[12:13], v[12:13], v[22:23] op_sel_hi:[1,0]
	v_lshl_add_u64 v[20:21], v[20:21], 0, v[114:115]
	v_mul_f32_e32 v23, 0xbfb8aa3b, v12
	v_exp_f32_e32 v23, v23
	global_store_dwordx4 v[20:21], v[16:19], off nt
	s_andn2_b64 vcc, exec, s[6:7]
	s_mov_b64 s[6:7], -1
	v_mul_f32_e32 v16, 0xbfb8aa3b, v13
	v_pk_mul_f32 v[14:15], v[14:15], v[22:23] op_sel_hi:[1,0]
	v_exp_f32_e32 v17, v16
	v_mul_f32_e32 v18, 0xbfb8aa3b, v14
	v_mul_f32_e32 v19, 0xbfb8aa3b, v15
	v_exp_f32_e32 v18, v18
	v_exp_f32_e32 v19, v19
	v_add_f32_e32 v16, 1.0, v23
	v_add_f32_e32 v17, 1.0, v17
	v_rcp_f32_e32 v16, v16
	v_rcp_f32_e32 v17, v17
	v_add_f32_e32 v18, 1.0, v18
	v_add_f32_e32 v19, 1.0, v19
	v_rcp_f32_e32 v18, v18
	v_rcp_f32_e32 v19, v19
	v_pk_mul_f32 v[8:9], v[8:9], v[22:23] op_sel_hi:[1,0]
	v_pk_mul_f32 v[12:13], v[12:13], v[16:17]
	v_pk_mul_f32 v[4:5], v[4:5], v[22:23] op_sel_hi:[1,0]
	v_pk_mul_f32 v[8:9], v[8:9], v[12:13]
	v_pk_mul_f32 v[12:13], v[14:15], v[18:19]
	v_mul_f32_e32 v14, 0xbfb8aa3b, v4
	v_exp_f32_e32 v14, v14
	v_pk_mul_f32 v[10:11], v[10:11], v[22:23] op_sel_hi:[1,0]
	v_pk_mul_f32 v[6:7], v[6:7], v[22:23] op_sel_hi:[1,0]
	v_pk_mul_f32 v[10:11], v[10:11], v[12:13]
	v_mul_f32_e32 v12, 0xbfb8aa3b, v5
	v_exp_f32_e32 v13, v12
	v_add_f32_e32 v12, 1.0, v14
	v_mul_f32_e32 v14, 0xbfb8aa3b, v6
	v_mul_f32_e32 v15, 0xbfb8aa3b, v7
	v_exp_f32_e32 v14, v14
	v_exp_f32_e32 v15, v15
	v_add_f32_e32 v13, 1.0, v13
	v_rcp_f32_e32 v12, v12
	v_rcp_f32_e32 v13, v13
	v_add_f32_e32 v14, 1.0, v14
	v_add_f32_e32 v15, 1.0, v15
	v_rcp_f32_e32 v14, v14
	v_rcp_f32_e32 v15, v15
	v_pk_mul_f32 v[0:1], v[0:1], v[22:23] op_sel_hi:[1,0]
	v_pk_mul_f32 v[4:5], v[4:5], v[12:13]
	v_add_u32_e32 v12, 0xb0, v208
	v_pk_mul_f32 v[4:5], v[0:1], v[4:5]
	v_pk_mul_f32 v[0:1], v[2:3], v[22:23] op_sel_hi:[1,0]
	v_pk_mul_f32 v[2:3], v[6:7], v[14:15]
	s_nop 0
	v_pk_mul_f32 v[6:7], v[0:1], v[2:3]
	v_cvt_pk_bf16_f32 v2, v4, v5
	v_mad_i64_i32 v[4:5], s[26:27], v12, s55, v[112:113]
	v_cvt_pk_bf16_f32 v0, v8, v9
	v_cvt_pk_bf16_f32 v1, v10, v11
	v_cvt_pk_bf16_f32 v3, v6, v7
	v_lshl_add_u64 v[4:5], v[4:5], 0, v[114:115]
	global_store_dwordx4 v[4:5], v[0:3], off nt
	s_cbranch_vccnz .LBB0_1350
	s_andn2_b64 vcc, exec, s[12:13]
	s_cbranch_vccnz .LBB0_1349
	s_barrier
	s_branch .LBB0_1349
